# conv block staging: 8 masked loads in flight into dead accumulator registers, one wait, 8 LDS writes (was 8 serialized load/wait/write round trips)
# speedup vs baseline: 1.0039x; 1.0028x over previous
; #define LAS __attribute__((address_space(3)))
; DI void conv_block(LAS unsigned char* lds, int b, int tb, int tid, const bf16_t* U, const float* cb, const float* lg, const float* lb, bf16_t* CC) {
;     ...
;     for (int i = tid; i < 62 * 64; i += 512) {
;         const int row = i >> 6, part = i & 63, ts = t00 - 30 + row;
;         u32x4 v = {0u, 0u, 0u, 0u};
;         if (ts >= 0) v = *(const u32x4*)(U + ((size_t)b * S_ + ts) * 512 + part * 8);
;         *(LAS u32x4*)(ut + row * 1024 + part * 16) = v;
;     }
.LBB0_1175:
	s_lshl_b32 s1, s8, 5
	s_ashr_i32 s0, s8, 7
	v_readfirstlane_b32 s10, v170
	s_and_b32 s9, s1, 0xfe0
	s_waitcnt lgkmcnt(0)
	s_barrier
	s_and_saveexec_b64 s[2:3], vcc
	s_cbranch_execz .LBB0_1180
	s_ashr_i32 s1, s0, 31
	s_lshl_b64 s[4:5], s[0:1], 22
	s_sub_i32 s11, s9, 30
	v_lshl_add_u64 v[4:5], v[24:25], 0, s[4:5]
	v_ashrrev_i32_e32 v7, 6, v170
	s_add_i32 s1, s11, 0
	v_add_u32_e32 v160, s1, v7
	v_cmp_lt_i32_e64 s[38:39], -1, v160
	v_mov_b32_e32 v34, 0
	v_mov_b32_e32 v35, 0
	v_mov_b32_e32 v36, 0
	v_mov_b32_e32 v37, 0
	s_and_saveexec_b64 s[6:7], s[38:39]
	v_lshlrev_b64 v[0:1], 10, v[160:161]
	v_lshl_add_u64 v[0:1], v[4:5], 0, v[0:1]
	global_load_dwordx4 v[34:37], v[0:1], off
	s_or_b64 exec, exec, s[6:7]
	s_add_i32 s1, s11, 8
	v_add_u32_e32 v160, s1, v7
	v_cmp_lt_i32_e64 s[38:39], -1, v160
	v_mov_b32_e32 v38, 0
	v_mov_b32_e32 v39, 0
	v_mov_b32_e32 v40, 0
	v_mov_b32_e32 v41, 0
	s_and_saveexec_b64 s[6:7], s[38:39]
	v_lshlrev_b64 v[0:1], 10, v[160:161]
	v_lshl_add_u64 v[0:1], v[4:5], 0, v[0:1]
	global_load_dwordx4 v[38:41], v[0:1], off
	s_or_b64 exec, exec, s[6:7]
	s_add_i32 s1, s11, 16
	v_add_u32_e32 v160, s1, v7
	v_cmp_lt_i32_e64 s[38:39], -1, v160
	v_mov_b32_e32 v42, 0
	v_mov_b32_e32 v43, 0
	v_mov_b32_e32 v44, 0
	v_mov_b32_e32 v45, 0
	s_and_saveexec_b64 s[6:7], s[38:39]
	v_lshlrev_b64 v[0:1], 10, v[160:161]
	v_lshl_add_u64 v[0:1], v[4:5], 0, v[0:1]
	global_load_dwordx4 v[42:45], v[0:1], off
	s_or_b64 exec, exec, s[6:7]
	s_add_i32 s1, s11, 24
	v_add_u32_e32 v160, s1, v7
	v_cmp_lt_i32_e64 s[38:39], -1, v160
	v_mov_b32_e32 v46, 0
	v_mov_b32_e32 v47, 0
	v_mov_b32_e32 v48, 0
	v_mov_b32_e32 v49, 0
	s_and_saveexec_b64 s[6:7], s[38:39]
	v_lshlrev_b64 v[0:1], 10, v[160:161]
	v_lshl_add_u64 v[0:1], v[4:5], 0, v[0:1]
	global_load_dwordx4 v[46:49], v[0:1], off
	s_or_b64 exec, exec, s[6:7]
	s_add_i32 s1, s11, 32
	v_add_u32_e32 v160, s1, v7
	v_cmp_lt_i32_e64 s[38:39], -1, v160
	v_mov_b32_e32 v50, 0
	v_mov_b32_e32 v51, 0
	v_mov_b32_e32 v52, 0
	v_mov_b32_e32 v53, 0
	s_and_saveexec_b64 s[6:7], s[38:39]
	v_lshlrev_b64 v[0:1], 10, v[160:161]
	v_lshl_add_u64 v[0:1], v[4:5], 0, v[0:1]
	global_load_dwordx4 v[50:53], v[0:1], off
	s_or_b64 exec, exec, s[6:7]
	s_add_i32 s1, s11, 40
	v_add_u32_e32 v160, s1, v7
	v_cmp_lt_i32_e64 s[38:39], -1, v160
	v_mov_b32_e32 v54, 0
	v_mov_b32_e32 v55, 0
	v_mov_b32_e32 v56, 0
	v_mov_b32_e32 v57, 0
	s_and_saveexec_b64 s[6:7], s[38:39]
	v_lshlrev_b64 v[0:1], 10, v[160:161]
	v_lshl_add_u64 v[0:1], v[4:5], 0, v[0:1]
	global_load_dwordx4 v[54:57], v[0:1], off
	s_or_b64 exec, exec, s[6:7]
	s_add_i32 s1, s11, 48
	v_add_u32_e32 v160, s1, v7
	v_cmp_lt_i32_e64 s[38:39], -1, v160
	v_mov_b32_e32 v58, 0
	v_mov_b32_e32 v59, 0
	v_mov_b32_e32 v60, 0
	v_mov_b32_e32 v61, 0
	s_and_saveexec_b64 s[6:7], s[38:39]
	v_lshlrev_b64 v[0:1], 10, v[160:161]
	v_lshl_add_u64 v[0:1], v[4:5], 0, v[0:1]
	global_load_dwordx4 v[58:61], v[0:1], off
	s_or_b64 exec, exec, s[6:7]
	s_add_i32 s1, s11, 56
	v_add_u32_e32 v160, s1, v7
	v_cmp_lt_i32_e64 s[38:39], -1, v160
	v_mov_b32_e32 v62, 0
	v_mov_b32_e32 v63, 0
	v_mov_b32_e32 v64, 0
	v_mov_b32_e32 v65, 0
	s_movk_i32 s1, 0x180
	v_cmp_gt_u32_e64 s[4:5], s1, v170
	s_and_b64 s[38:39], s[38:39], s[4:5]
	s_and_saveexec_b64 s[6:7], s[38:39]
	v_lshlrev_b64 v[0:1], 10, v[160:161]
	v_lshl_add_u64 v[0:1], v[4:5], 0, v[0:1]
	global_load_dwordx4 v[62:65], v[0:1], off
	s_or_b64 exec, exec, s[6:7]
	v_lshl_add_u32 v7, v7, 10, v74
	s_waitcnt vmcnt(0)
	ds_write_b128 v7, v[34:37]
	ds_write_b128 v7, v[38:41] offset:8192
	ds_write_b128 v7, v[42:45] offset:16384
	ds_write_b128 v7, v[46:49] offset:24576
	ds_write_b128 v7, v[50:53] offset:32768
	ds_write_b128 v7, v[54:57] offset:40960
	ds_write_b128 v7, v[58:61] offset:49152
	s_movk_i32 s1, 0x180
	v_cmp_gt_u32_e64 s[4:5], s1, v170
	s_and_saveexec_b64 s[6:7], s[4:5]
	ds_write_b128 v7, v[62:65] offset:57344
	s_or_b64 exec, exec, s[6:7]
